# MLA loop: waves 4-7 run a copy of the loop with s_setprio levels 1/2 instead of 0/1 (static priority bias for the second-dispatched half, per-cluster flips kept)
# baseline (speedup 1.0000x reference)
.LBB0_554:
	s_setprio 0
	v_mov_b32_e32 v0, v141
	s_nop 1
	v_permlane16_swap_b32_e32 v0, v141
	v_readlane_b32 s4, v254, 38
	v_readlane_b32 s5, v254, 39
	s_add_i32 s6, s6, 1
	s_cmp_eq_u32 s6, 8
	v_add_f32_e32 v0, v141, v0
	v_mov_b32_e32 v2, v0
	s_nop 1
	v_permlane32_swap_b32_e32 v2, v0
	v_add_f32_e32 v0, v0, v2
	v_div_scale_f32 v4, s[2:3], v0, v0, 1.0
	v_rcp_f32_e32 v5, v4
	v_div_scale_f32 v6, vcc, 1.0, v0, 1.0
	v_lshlrev_b64 v[2:3], 11, v[112:113]
	v_fma_f32 v7, -v4, v5, 1.0
	v_fmac_f32_e32 v5, v7, v5
	v_mul_f32_e32 v7, v6, v5
	v_fma_f32 v8, -v4, v7, v6
	v_fmac_f32_e32 v7, v8, v5
	v_fma_f32 v4, -v4, v7, v6
	v_div_fmas_f32 v4, v4, v5, v7
	v_div_fixup_f32 v4, v4, v0, 1.0
	v_pk_mul_f32 v[8:9], v[76:77], v[4:5] op_sel_hi:[1,0]
	v_pk_mul_f32 v[6:7], v[74:75], v[4:5] op_sel_hi:[1,0]
	v_bfe_u32 v0, v9, 16, 1
	v_bfe_u32 v5, v8, 16, 1
	v_add3_u32 v5, v8, v5, s0
	v_add3_u32 v0, v9, v0, s0
	v_mov_b32_e32 v10, v7
	v_perm_b32 v7, v0, v5, s19
	v_lshl_add_u64 v[2:3], s[4:5], 0, v[2:3]
	v_lshlrev_b32_e32 v0, 1, v131
	v_cvt_pk_bf16_f32 v6, v6, v10
	v_lshl_add_u64 v[2:3], v[2:3], 0, v[0:1]
	global_store_dwordx2 v[2:3], v[6:7], off
	v_pk_mul_f32 v[6:7], v[70:71], v[4:5] op_sel_hi:[1,0]
	v_pk_mul_f32 v[8:9], v[72:73], v[4:5] op_sel_hi:[1,0]
	v_bfe_u32 v5, v9, 16, 1
	v_bfe_u32 v10, v8, 16, 1
	v_mov_b32_e32 v11, v7
	v_add3_u32 v7, v8, v10, s0
	v_add3_u32 v5, v9, v5, s0
	v_perm_b32 v7, v5, v7, s19
	v_cvt_pk_bf16_f32 v6, v6, v11
	global_store_dwordx2 v[2:3], v[6:7], off offset:32
	v_pk_mul_f32 v[6:7], v[66:67], v[4:5] op_sel_hi:[1,0]
	v_pk_mul_f32 v[8:9], v[68:69], v[4:5] op_sel_hi:[1,0]
	v_bfe_u32 v10, v8, 16, 1
	v_mov_b32_e32 v11, v7
	v_add3_u32 v7, v8, v10, s0
	v_mov_b32_e32 v8, v140
	s_nop 1
	v_permlane16_swap_b32_e32 v8, v140
	v_bfe_u32 v5, v9, 16, 1
	v_add3_u32 v5, v9, v5, s0
	v_add_f32_e32 v8, v140, v8
	v_mov_b32_e32 v13, v8
	s_nop 1
	v_permlane32_swap_b32_e32 v13, v8
	v_perm_b32 v7, v5, v7, s19
	v_cvt_pk_bf16_f32 v6, v6, v11
	global_store_dwordx2 v[2:3], v[6:7], off offset:64
	v_pk_mul_f32 v[6:7], v[62:63], v[4:5] op_sel_hi:[1,0]
	v_pk_mul_f32 v[4:5], v[64:65], v[4:5] op_sel_hi:[1,0]
	v_add_f32_e32 v8, v8, v13
	v_div_scale_f32 v9, s[2:3], v8, v8, 1.0
	v_rcp_f32_e32 v10, v9
	v_cvt_pk_bf16_f32 v5, v4, v5
	v_cvt_pk_bf16_f32 v4, v6, v7
	global_store_dwordx2 v[2:3], v[4:5], off offset:96
	v_fma_f32 v2, -v9, v10, 1.0
	v_fmac_f32_e32 v10, v2, v10
	v_div_scale_f32 v2, vcc, 1.0, v8, 1.0
	v_mul_f32_e32 v3, v2, v10
	v_fma_f32 v4, -v9, v3, v2
	v_fmac_f32_e32 v3, v4, v10
	v_fma_f32 v2, -v9, v3, v2
	v_div_fmas_f32 v2, v2, v10, v3
	v_div_fixup_f32 v2, v2, v8, 1.0
	v_pk_mul_f32 v[6:7], v[58:59], v[2:3] op_sel_hi:[1,0]
	v_pk_mul_f32 v[8:9], v[60:61], v[2:3] op_sel_hi:[1,0]
	v_lshlrev_b64 v[4:5], 11, v[110:111]
	v_bfe_u32 v3, v9, 16, 1
	v_bfe_u32 v10, v8, 16, 1
	v_mov_b32_e32 v11, v7
	v_add3_u32 v7, v8, v10, s0
	v_add3_u32 v3, v9, v3, s0
	v_lshl_add_u64 v[4:5], s[4:5], 0, v[4:5]
	v_perm_b32 v7, v3, v7, s19
	v_cvt_pk_bf16_f32 v6, v6, v11
	v_lshl_add_u64 v[4:5], v[4:5], 0, v[0:1]
	global_store_dwordx2 v[4:5], v[6:7], off
	v_pk_mul_f32 v[6:7], v[54:55], v[2:3] op_sel_hi:[1,0]
	v_pk_mul_f32 v[8:9], v[56:57], v[2:3] op_sel_hi:[1,0]
	v_bfe_u32 v0, v9, 16, 1
	v_bfe_u32 v3, v8, 16, 1
	v_mov_b32_e32 v10, v7
	v_add3_u32 v3, v8, v3, s0
	v_add3_u32 v0, v9, v0, s0
	v_perm_b32 v7, v0, v3, s19
	v_cvt_pk_bf16_f32 v6, v6, v10
	global_store_dwordx2 v[4:5], v[6:7], off offset:32
	v_pk_mul_f32 v[6:7], v[50:51], v[2:3] op_sel_hi:[1,0]
	v_pk_mul_f32 v[8:9], v[52:53], v[2:3] op_sel_hi:[1,0]
	v_bfe_u32 v0, v9, 16, 1
	v_bfe_u32 v3, v8, 16, 1
	v_mov_b32_e32 v10, v7
	v_add3_u32 v3, v8, v3, s0
	v_add3_u32 v0, v9, v0, s0
	v_perm_b32 v7, v0, v3, s19
	v_cvt_pk_bf16_f32 v6, v6, v10
	global_store_dwordx2 v[4:5], v[6:7], off offset:64
	v_pk_mul_f32 v[6:7], v[46:47], v[2:3] op_sel_hi:[1,0]
	v_pk_mul_f32 v[2:3], v[48:49], v[2:3] op_sel_hi:[1,0]
	v_cvt_pk_bf16_f32 v3, v2, v3
	v_cvt_pk_bf16_f32 v2, v6, v7
	global_store_dwordx2 v[4:5], v[2:3], off offset:96
	s_cbranch_scc1 .LBB0_588
.LBB0_555:
	s_lshl_b32 s2, s6, 4
	s_add_i32 s2, s7, s2
	s_ashr_i32 s3, s2, 4
	v_mov_b32_e32 v58, v163
	s_mul_i32 s2, s3, 0x1100
	v_readlane_b32 s4, v253, 36
	s_add_i32 s4, s4, s2
	v_and_b32_e32 v125, 15, v58
	v_ashrrev_i32_e32 v0, 1, v58
	v_bfe_u32 v59, v58, 4, 2
	v_and_b32_e32 v0, 0xffffffe0, v0
	s_waitcnt vmcnt(3)
	v_or_b32_e32 v2, s4, v125
	v_readlane_b32 s4, v254, 16
	v_add_u32_e32 v112, v2, v0
	v_lshlrev_b32_e32 v0, 4, v59
	v_readlane_b32 s5, v254, 17
	s_movk_i32 s8, 0xc00
	s_mulk_i32 s3, 0xef00
	v_lshl_add_u64 v[30:31], s[4:5], 0, v[0:1]
	s_waitcnt vmcnt(2)
	v_mad_i64_i32 v[6:7], s[4:5], v112, s8, v[30:31]
	s_waitcnt lgkmcnt(0)
	global_load_dwordx4 v[10:13], v[6:7], off offset:128
	s_addk_i32 s3, 0xff00
	v_add_u32_e32 v2, s3, v112
	v_ashrrev_i32_e32 v32, 6, v2
	v_and_b32_e32 v2, 47, v112
	v_cmp_gt_u32_e32 vcc, 2, v59
	v_readlane_b32 s40, v254, 55
	v_readlane_b32 s50, v255, 1
	v_cndmask_b32_e32 v2, v2, v32, vcc
	v_lshlrev_b32_e32 v2, 4, v2
	v_ashrrev_i32_e32 v3, 31, v2
	v_readlane_b32 s51, v255, 2
	v_cmp_lt_i32_e64 s[4:5], v198, v196
	v_or_b32_e32 v110, 16, v112
	v_lshl_add_u64 v[2:3], v[2:3], 2, s[50:51]
	global_load_dwordx4 v[14:17], v[2:3], off
	global_load_dwordx4 v[18:21], v[2:3], off offset:16
	global_load_dwordx4 v[22:25], v[2:3], off offset:32
	global_load_dwordx4 v[26:29], v[2:3], off offset:48
	v_cndmask_b32_e64 v2, v195, v198, s[4:5]
	v_mad_i64_i32 v[30:31], s[4:5], v110, s8, v[30:31]
	v_lshlrev_b32_e32 v124, 2, v2
	v_bitop3_b32 v33, v112, 63, 16 bitop3:0xc8
	global_load_dwordx4 v[2:5], v[6:7], off
	s_nop 0
	global_load_dwordx4 v[6:9], v[6:7], off offset:64
	v_cndmask_b32_e32 v32, v33, v32, vcc
	global_load_dwordx4 v[42:45], v[30:31], off offset:128
	v_lshlrev_b32_e32 v32, 4, v32
	v_ashrrev_i32_e32 v33, 31, v32
	v_lshl_add_u64 v[32:33], v[32:33], 2, s[50:51]
	global_load_dwordx4 v[38:41], v[32:33], off offset:48
	global_load_dwordx4 v[46:49], v[32:33], off offset:32
	global_load_dwordx4 v[50:53], v[32:33], off offset:16
	global_load_dwordx4 v[54:57], v[32:33], off
	v_and_b32_e32 v68, 16, v58
	v_cmp_eq_u32_e32 vcc, 0, v68
	v_ashrrev_i32_e32 v126, 3, v58
	v_readlane_b32 s4, v254, 18
	v_readlane_b32 s5, v254, 19
	v_readlane_b32 s8, v254, 36
	v_mov_b32_e32 v115, v1
	v_readlane_b32 s9, v254, 37
	v_ashrrev_i32_e32 v128, 2, v58
	v_readlane_b32 s41, v254, 56
	v_readlane_b32 s42, v254, 57
	v_readlane_b32 s43, v254, 58
	v_readlane_b32 s44, v254, 59
	v_readlane_b32 s45, v254, 60
	v_readlane_b32 s46, v254, 61
	v_readlane_b32 s47, v254, 62
	v_readlane_b32 s48, v254, 63
	v_readlane_b32 s49, v255, 0
	v_readlane_b32 s52, v255, 3
	v_readlane_b32 s53, v255, 4
	v_readlane_b32 s54, v255, 5
	v_readlane_b32 s55, v255, 6
	v_readlane_b32 s40, v252, 16
	v_readlane_b32 s42, v252, 18
	v_readlane_b32 s43, v252, 19
	v_mov_b32_e32 v117, v1
	s_waitcnt vmcnt(12)
	v_lshlrev_b32_e32 v131, 2, v59
	v_ashrrev_i32_e32 v113, 31, v112
	v_ashrrev_i32_e32 v111, 31, v110
	v_mov_b32_e32 v140, 0
	v_mov_b32_e32 v138, 0xf149f2ca
	v_mov_b32_e32 v139, 0xf149f2ca
	v_mov_b32_e32 v141, 0
	v_readlane_b32 s41, v252, 17
	v_readlane_b32 s44, v252, 20
	v_readlane_b32 s45, v252, 21
	v_readlane_b32 s46, v252, 22
	v_readlane_b32 s47, v252, 23
	v_readlane_b32 s48, v252, 24
	v_readlane_b32 s49, v252, 25
	v_readlane_b32 s50, v252, 26
	v_readlane_b32 s51, v252, 27
	v_readlane_b32 s52, v252, 28
	v_readlane_b32 s53, v252, 29
	v_readlane_b32 s54, v252, 30
	v_readlane_b32 s55, v252, 31
	s_waitcnt vmcnt(11)
	v_and_b32_e32 v33, 0xffff0000, v10
	v_lshlrev_b32_e32 v32, 16, v10
	v_and_b32_e32 v35, 0xffff0000, v11
	v_lshlrev_b32_e32 v34, 16, v11
	v_and_b32_e32 v11, 0xffff0000, v12
	v_lshlrev_b32_e32 v10, 16, v12
	v_and_b32_e32 v37, 0xffff0000, v13
	v_lshlrev_b32_e32 v36, 16, v13
	ds_bpermute_b32 v12, v124, v32
	ds_bpermute_b32 v13, v124, v33
	ds_bpermute_b32 v60, v124, v34
	ds_bpermute_b32 v61, v124, v35
	ds_bpermute_b32 v62, v124, v10
	ds_bpermute_b32 v63, v124, v11
	s_waitcnt vmcnt(10)
	v_mov_b32_e32 v67, v16
	v_mov_b32_e32 v16, v15
	s_waitcnt vmcnt(9)
	v_mov_b32_e32 v15, v20
	v_mov_b32_e32 v20, v19
	s_waitcnt vmcnt(8)
	v_mov_b32_e32 v19, v24
	v_mov_b32_e32 v24, v23
	s_waitcnt lgkmcnt(4)
	v_pk_mul_f32 v[12:13], v[16:17], v[12:13]
	s_waitcnt lgkmcnt(2)
	v_pk_mul_f32 v[16:17], v[20:21], v[60:61]
	ds_bpermute_b32 v64, v124, v36
	ds_bpermute_b32 v65, v124, v37
	v_mov_b32_e32 v66, v14
	v_mov_b32_e32 v14, v18
	s_waitcnt lgkmcnt(2)
	v_pk_mul_f32 v[20:21], v[24:25], v[62:63]
	v_cndmask_b32_e64 v17, v17, -v17, vcc
	v_cndmask_b32_e64 v16, v16, -v16, vcc
	v_mov_b32_e32 v18, v22
	v_cndmask_b32_e64 v13, v13, -v13, vcc
	v_cndmask_b32_e64 v12, v12, -v12, vcc
	v_cndmask_b32_e64 v21, v21, -v21, vcc
	v_cndmask_b32_e64 v20, v20, -v20, vcc
	v_pk_fma_f32 v[14:15], v[14:15], v[34:35], v[16:17]
	v_pk_fma_f32 v[12:13], v[66:67], v[32:33], v[12:13]
	v_pk_fma_f32 v[10:11], v[18:19], v[10:11], v[20:21]
	v_add_u32_e32 v60, s2, v126
	v_mov_b32_e32 v75, v15
	v_ashrrev_i32_e32 v61, 31, v60
	v_add_u32_e32 v18, 0x200, v58
	s_waitcnt vmcnt(7)
	v_mov_b32_e32 v23, v28
	v_mov_b32_e32 v28, v27
	v_mov_b32_e32 v72, v12
	v_mov_b32_e32 v74, v14
	v_lshlrev_b64 v[14:15], 11, v[60:61]
	v_lshlrev_b32_e32 v12, 4, v58
	v_ashrrev_i32_e32 v127, 3, v18
	s_waitcnt lgkmcnt(0)
	v_pk_mul_f32 v[24:25], v[28:29], v[64:65]
	v_mov_b32_e32 v76, v10
	v_mov_b32_e32 v77, v11
	v_lshl_add_u64 v[10:11], s[4:5], 0, v[14:15]
	v_and_b32_e32 v114, 0x70, v12
	v_add_u32_e32 v62, s2, v127
	v_mov_b32_e32 v22, v26
	v_cndmask_b32_e64 v25, v25, -v25, vcc
	v_cndmask_b32_e64 v24, v24, -v24, vcc
	v_lshl_add_u64 v[10:11], v[10:11], 0, v[114:115]
	v_lshl_add_u64 v[14:15], s[8:9], 0, v[14:15]
	v_ashrrev_i32_e32 v63, 31, v62
	v_pk_fma_f32 v[26:27], v[22:23], v[36:37], v[24:25]
	v_mov_b32_e32 v73, v13
	global_load_dwordx4 v[10:13], v[10:11], off
	v_lshl_add_u64 v[14:15], v[14:15], 0, v[114:115]
	v_lshlrev_b64 v[22:23], 11, v[62:63]
	v_add_u32_e32 v64, s2, v128
	v_lshlrev_b32_e32 v34, 3, v58
	global_load_dwordx4 v[14:17], v[14:15], off
	v_lshl_add_u64 v[18:19], s[4:5], 0, v[22:23]
	v_ashrrev_i32_e32 v65, 31, v64
	v_lshl_add_u64 v[18:19], v[18:19], 0, v[114:115]
	v_lshl_add_u64 v[22:23], s[8:9], 0, v[22:23]
	v_lshlrev_b64 v[28:29], 6, v[64:65]
	v_and_b32_e32 v130, 24, v34
	global_load_dwordx4 v[18:21], v[18:19], off
	v_lshl_add_u64 v[22:23], v[22:23], 0, v[114:115]
	v_lshl_add_u64 v[28:29], s[42:43], 0, v[28:29]
	v_lshlrev_b32_e32 v116, 1, v130
	global_load_dwordx4 v[22:25], v[22:23], off
	v_lshl_add_u64 v[28:29], v[28:29], 0, v[116:117]
	global_load_dwordx4 v[34:37], v[28:29], off
	v_mov_b32_e32 v61, v26
	v_mov_b32_e32 v63, v27
	global_load_dwordx4 v[26:29], v[30:31], off
	s_nop 0
	global_load_dwordx4 v[30:33], v[30:31], off offset:64
	s_waitcnt vmcnt(11)
	v_and_b32_e32 v67, 0xffff0000, v42
	v_lshlrev_b32_e32 v66, 16, v42
	ds_bpermute_b32 v68, v124, v66
	ds_bpermute_b32 v69, v124, v67
	s_waitcnt vmcnt(7)
	v_mov_b32_e32 v71, v56
	v_mov_b32_e32 v56, v55
	v_mov_b32_e32 v70, v54
	v_lshl_add_u64 v[118:119], s[4:5], 0, v[114:115]
	s_waitcnt lgkmcnt(0)
	v_pk_mul_f32 v[54:55], v[56:57], v[68:69]
	v_and_b32_e32 v57, 0xffff0000, v43
	v_lshlrev_b32_e32 v56, 16, v43
	ds_bpermute_b32 v42, v124, v56
	ds_bpermute_b32 v43, v124, v57
	v_cndmask_b32_e64 v55, v55, -v55, vcc
	v_cndmask_b32_e64 v54, v54, -v54, vcc
	v_pk_fma_f32 v[54:55], v[70:71], v[66:67], v[54:55]
	v_mov_b32_e32 v66, v50
	v_mov_b32_e32 v67, v52
	v_mov_b32_e32 v52, v51
	v_and_b32_e32 v51, 0xffff0000, v44
	v_lshlrev_b32_e32 v50, 16, v44
	s_waitcnt lgkmcnt(0)
	v_pk_mul_f32 v[42:43], v[52:53], v[42:43]
	ds_bpermute_b32 v52, v124, v50
	ds_bpermute_b32 v53, v124, v51
	v_cndmask_b32_e64 v43, v43, -v43, vcc
	v_cndmask_b32_e64 v42, v42, -v42, vcc
	v_pk_fma_f32 v[42:43], v[66:67], v[56:57], v[42:43]
	v_mov_b32_e32 v57, v48
	v_mov_b32_e32 v48, v47
	v_mov_b32_e32 v56, v46
	s_waitcnt lgkmcnt(0)
	v_pk_mul_f32 v[46:47], v[48:49], v[52:53]
	v_and_b32_e32 v49, 0xffff0000, v45
	v_lshlrev_b32_e32 v48, 16, v45
	ds_bpermute_b32 v44, v124, v48
	ds_bpermute_b32 v45, v124, v49
	v_cndmask_b32_e64 v47, v47, -v47, vcc
	v_cndmask_b32_e64 v46, v46, -v46, vcc
	v_pk_fma_f32 v[46:47], v[56:57], v[50:51], v[46:47]
	v_mov_b32_e32 v51, v40
	v_mov_b32_e32 v40, v39
	v_mov_b32_e32 v50, v38
	s_waitcnt lgkmcnt(0)
	v_pk_mul_f32 v[38:39], v[40:41], v[44:45]
	v_cndmask_b32_e64 v39, v39, -v39, vcc
	v_cndmask_b32_e64 v38, v38, -v38, vcc
	v_pk_fma_f32 v[38:39], v[50:51], v[48:49], v[38:39]
	v_mov_b32_e32 v44, v47
	v_mov_b32_e32 v45, v38
	v_mov_b32_e32 v47, v39
	v_mad_u64_u32 v[38:39], s[2:3], v126, s12, v[114:115]
	v_lshlrev_b32_e32 v39, 6, v126
	s_waitcnt vmcnt(6)
	ds_write_b128 v38, v[10:13]
	v_sub_u32_e32 v38, v38, v39
	v_cmp_lt_i32_e32 vcc, v197, v196
	s_waitcnt vmcnt(5)
	ds_write_b128 v38, v[14:17] offset:53248
	v_mad_u64_u32 v[38:39], s[2:3], v127, s12, v[114:115]
	v_lshlrev_b32_e32 v39, 6, v127
	s_waitcnt vmcnt(4)
	ds_write_b128 v38, v[18:21]
	v_sub_u32_e32 v38, v38, v39
	s_waitcnt vmcnt(3)
	ds_write_b128 v38, v[22:25] offset:53248
	v_mad_u64_u32 v[38:39], s[2:3], v128, s12, v[116:117]
	s_waitcnt vmcnt(2)
	ds_write_b128 v38, v[34:37] offset:128
	v_cndmask_b32_e32 v38, v195, v197, vcc
	v_lshlrev_b32_e32 v129, 2, v38
	v_bfe_u32 v38, v58, 2, 2
	v_mov_b32_e32 v48, v1
	v_mov_b32_e32 v49, v1
	v_or_b32_e32 v132, v131, v38
	v_cvt_pk_bf16_f32 v41, v61, v63
	v_cvt_pk_bf16_f32 v40, v76, v77
	v_cvt_pk_bf16_f32 v39, v74, v75
	v_cvt_pk_bf16_f32 v38, v72, v73
	v_cvt_pk_bf16_f32 v45, v45, v47
	v_cvt_pk_bf16_f32 v44, v46, v44
	v_cvt_pk_bf16_f32 v43, v42, v43
	v_cvt_pk_bf16_f32 v42, v54, v55
	v_lshl_add_u64 v[120:121], s[8:9], 0, v[114:115]
	v_lshl_add_u64 v[122:123], s[42:43], 0, v[116:117]
	v_add_u32_e32 v115, 0x80, v64
	v_add_u32_e32 v117, 0x80, v62
	v_add_u32_e32 v137, 0x80, v60
	v_mov_b32_e32 v46, v1
	v_mov_b32_e32 v47, v1
	v_mov_b64_e32 v[64:65], v[48:49]
	v_mov_b64_e32 v[52:53], v[48:49]
	v_mov_b64_e32 v[68:69], v[48:49]
	v_mov_b64_e32 v[56:57], v[48:49]
	v_mov_b64_e32 v[72:73], v[48:49]
	v_mov_b64_e32 v[60:61], v[48:49]
	v_mov_b64_e32 v[76:77], v[48:49]
	v_or_b32_e32 v133, 0xd000, v130
	v_or_b32_e32 v134, 0xd020, v130
	v_or_b32_e32 v135, 0xd040, v130
	v_or_b32_e32 v136, 0xd060, v130
	s_mov_b32 s4, 0
	v_mov_b64_e32 v[62:63], v[46:47]
	v_mov_b64_e32 v[50:51], v[46:47]
	v_mov_b64_e32 v[66:67], v[46:47]
	v_mov_b64_e32 v[54:55], v[46:47]
	v_mov_b64_e32 v[70:71], v[46:47]
	v_mov_b64_e32 v[58:59], v[46:47]
	v_mov_b64_e32 v[74:75], v[46:47]
	v_mad_u32_u24 v224, v126, s12, v114
	v_mad_u32_u24 v225, v126, s16, v114
	v_mad_u32_u24 v226, v127, s12, v114
	v_mad_u32_u24 v227, v127, s16, v114
	v_mad_u32_u24 v228, v128, s12, v116
	v_add_u32_e32 v229, 0x4800, v225
	v_add_u32_e32 v230, 0x4800, v227
	s_waitcnt vmcnt(0)
	s_waitcnt lgkmcnt(0)
	s_barrier
	v_readfirstlane_b32 s100, v163
	s_bitcmp1_b32 s100, 8
	s_cbranch_scc0 .LBB0_557
	s_setprio 1
	s_branch .Lmlahi_BB0_557

.Lmla_stage_buf0:
	s_waitcnt vmcnt(4)
	ds_write_b128 v224, v[10:13]
	s_waitcnt vmcnt(3)
	ds_write_b128 v225, v[14:17] offset:53248
	s_waitcnt vmcnt(2)
	ds_write_b128 v226, v[18:21]
	s_waitcnt vmcnt(1)
	ds_write_b128 v227, v[22:25] offset:53248
	s_waitcnt vmcnt(0)
	ds_write_b128 v228, v[34:37] offset:128
	s_branch .LBB0_556
.Lmlahi_BB0_556:
	v_add_f32_e32 v90, 0, v90
	v_add_f32_e32 v90, v91, v90
	v_add_f32_e32 v90, v92, v90
	v_add_f32_e32 v90, v93, v90
	v_add_f32_e32 v82, v82, v90
	v_add_f32_e32 v82, v83, v82
	v_add_f32_e32 v82, v84, v82
	v_add_f32_e32 v82, v85, v82
	v_add_f32_e32 v82, v86, v82
	v_add_f32_e32 v82, v87, v82
	v_add_f32_e32 v82, v88, v82
	v_add_f32_e32 v82, v89, v82
	v_add_f32_e32 v78, v78, v82
	v_add_f32_e32 v78, v79, v78
	v_add_f32_e32 v78, v80, v78
	v_add_f32_e32 v78, v81, v78
	v_add_f32_e32 v140, v140, v78
	v_add_f32_e32 v78, 0, v106
	v_add_f32_e32 v78, v107, v78
	v_add_f32_e32 v78, v108, v78
	v_add_f32_e32 v78, v109, v78
	v_add_f32_e32 v78, v98, v78
	v_add_f32_e32 v78, v99, v78
	v_add_f32_e32 v78, v100, v78
	v_add_f32_e32 v78, v101, v78
	v_add_f32_e32 v78, v102, v78
	v_add_f32_e32 v78, v103, v78
	v_add_f32_e32 v78, v104, v78
	v_add_f32_e32 v78, v105, v78
	v_add_f32_e32 v78, v94, v78
	v_add_f32_e32 v78, v95, v78
	v_add_f32_e32 v78, v96, v78
	v_add_f32_e32 v78, v97, v78
	s_addk_i32 s4, 0x80
	v_add_f32_e32 v141, v141, v78
	s_cmpk_lg_i32 s4, 0x1100
	s_waitcnt lgkmcnt(0)
	s_barrier
	s_cbranch_scc0 .LBB0_554

.Lmlahi_BB0_559:
	s_and_b32 s5, s4, 0x80
	v_or_b32_e32 v142, s5, v125
	v_mad_u32_u24 v143, v142, s12, v0
	ds_read_b128 v[78:81], v143
	ds_read_b128 v[82:85], v143 offset:64
	ds_read_b128 v[86:89], v143 offset:128
	ds_read_b128 v[94:97], v143 offset:3328
	ds_read_b128 v[98:101], v143 offset:3392
	ds_read_b128 v[144:147], v143 offset:3456
	s_setprio 2
	s_waitcnt lgkmcnt(5)
	v_mfma_f32_16x16x32_bf16 v[90:93], v[78:81], v[2:5], 0
	v_mfma_f32_16x16x32_bf16 v[78:81], v[78:81], v[26:29], 0
	s_waitcnt lgkmcnt(4)
	v_mfma_f32_16x16x32_bf16 v[90:93], v[82:85], v[6:9], v[90:93]
	v_mfma_f32_16x16x32_bf16 v[78:81], v[82:85], v[30:33], v[78:81]
	s_waitcnt lgkmcnt(3)
	v_mfma_f32_16x16x32_bf16 v[106:109], v[86:89], v[38:41], v[90:93]
	v_mfma_f32_16x16x32_bf16 v[90:93], v[86:89], v[42:45], v[78:81]
	s_waitcnt lgkmcnt(2)
	v_mfma_f32_16x16x32_bf16 v[78:81], v[94:97], v[2:5], 0
	v_mfma_f32_16x16x32_bf16 v[82:85], v[94:97], v[26:29], 0
	s_waitcnt lgkmcnt(1)
	v_mfma_f32_16x16x32_bf16 v[78:81], v[98:101], v[6:9], v[78:81]
	v_mfma_f32_16x16x32_bf16 v[82:85], v[98:101], v[30:33], v[82:85]
	s_waitcnt lgkmcnt(0)
	v_mfma_f32_16x16x32_bf16 v[102:105], v[144:147], v[38:41], v[78:81]
	v_mfma_f32_16x16x32_bf16 v[82:85], v[144:147], v[42:45], v[82:85]
	s_setprio 1
	s_nop 2
	ds_read_b128 v[78:81], v143 offset:6656
	ds_read_b128 v[86:89], v143 offset:6720
	ds_read_b128 v[94:97], v143 offset:6784
	ds_read_b128 v[144:147], v143 offset:9984
	ds_read_b128 v[148:151], v143 offset:10048
	ds_read_b128 v[152:155], v143 offset:10112
	s_setprio 2
	s_waitcnt lgkmcnt(5)
	v_mfma_f32_16x16x32_bf16 v[98:101], v[78:81], v[2:5], 0
	v_mfma_f32_16x16x32_bf16 v[78:81], v[78:81], v[26:29], 0
	s_waitcnt lgkmcnt(4)
	v_mfma_f32_16x16x32_bf16 v[98:101], v[86:89], v[6:9], v[98:101]
	v_mfma_f32_16x16x32_bf16 v[78:81], v[86:89], v[30:33], v[78:81]
	s_waitcnt lgkmcnt(3)
	v_mfma_f32_16x16x32_bf16 v[98:101], v[94:97], v[38:41], v[98:101]
	v_mfma_f32_16x16x32_bf16 v[86:89], v[94:97], v[42:45], v[78:81]
	s_waitcnt lgkmcnt(2)
	v_mfma_f32_16x16x32_bf16 v[78:81], v[144:147], v[2:5], 0
	v_mfma_f32_16x16x32_bf16 v[94:97], v[144:147], v[26:29], 0
	s_waitcnt lgkmcnt(1)
	v_mfma_f32_16x16x32_bf16 v[78:81], v[148:151], v[6:9], v[78:81]
	v_mfma_f32_16x16x32_bf16 v[144:147], v[148:151], v[30:33], v[94:97]
	s_waitcnt lgkmcnt(0)
	v_mfma_f32_16x16x32_bf16 v[94:97], v[152:155], v[38:41], v[78:81]
	v_mfma_f32_16x16x32_bf16 v[78:81], v[152:155], v[42:45], v[144:147]
	s_setprio 1
	v_max3_f32 v143, v106, s18, v107
	v_max3_f32 v143, v143, v108, v109
	v_max3_f32 v143, v143, v102, v103
	v_max3_f32 v143, v143, v104, v105
	v_max3_f32 v143, v143, v98, v99
	v_max3_f32 v143, v143, v100, v101
	v_max3_f32 v143, v143, v94, v95
	v_max3_f32 v143, v143, v96, v97
	v_mul_f32_e32 v143, 0x3e16c740, v143
	v_mov_b32_e32 v144, v143
	s_nop 1
	v_permlane16_swap_b32_e32 v144, v143
	v_max_f32_e32 v143, v143, v144
	v_mov_b32_e32 v144, v143
	s_nop 1
	v_permlane32_swap_b32_e32 v144, v143
	v_max_f32_e32 v143, v143, v144
	v_add_f32_e32 v144, 0x41000000, v139
	v_cmp_gt_f32_e32 vcc, v143, v144
	s_cbranch_vccz .Lmlahi_BB0_561
	v_max_f32_e32 v143, v143, v143
	v_max_f32_e32 v144, v139, v139
	v_max_f32_e32 v143, v144, v143
	v_sub_f32_e32 v139, v139, v143
	v_exp_f32_e32 v144, v139
	v_mov_b32_e32 v139, v143
	v_mul_f32_e32 v141, v141, v144
	v_pk_mul_f32 v[76:77], v[76:77], v[144:145] op_sel_hi:[1,0]
	v_pk_mul_f32 v[74:75], v[74:75], v[144:145] op_sel_hi:[1,0]
	v_pk_mul_f32 v[72:73], v[72:73], v[144:145] op_sel_hi:[1,0]
	v_pk_mul_f32 v[70:71], v[70:71], v[144:145] op_sel_hi:[1,0]
	v_pk_mul_f32 v[68:69], v[68:69], v[144:145] op_sel_hi:[1,0]
	v_pk_mul_f32 v[66:67], v[66:67], v[144:145] op_sel_hi:[1,0]
	v_pk_mul_f32 v[64:65], v[64:65], v[144:145] op_sel_hi:[1,0]
	v_pk_mul_f32 v[62:63], v[62:63], v[144:145] op_sel_hi:[1,0]

.Lmlahi_BB0_563:
	v_fma_f32 v106, v106, s21, -v139
	v_exp_f32_e32 v106, v106
	v_fma_f32 v107, v107, s21, -v139
	v_exp_f32_e32 v107, v107
	v_fma_f32 v108, v108, s21, -v139
	v_exp_f32_e32 v108, v108
	v_fma_f32 v109, v109, s21, -v139
	v_exp_f32_e32 v109, v109
	v_fma_f32 v102, v102, s21, -v139
	v_mul_u32_u24_e32 v160, 0xd0, v142
	v_add_f32_e32 v142, 0, v106
	v_exp_f32_e32 v102, v102
	v_fma_f32 v103, v103, s21, -v139
	v_add_f32_e32 v142, v107, v142
	v_exp_f32_e32 v103, v103
	v_fma_f32 v104, v104, s21, -v139
	v_add_f32_e32 v142, v108, v142
	v_exp_f32_e32 v104, v104
	v_fma_f32 v105, v105, s21, -v139
	v_add_f32_e32 v142, v109, v142
	v_exp_f32_e32 v105, v105
	v_fma_f32 v98, v98, s21, -v139
	v_cvt_pk_bf16_f32 v106, v106, v107
	v_cvt_pk_bf16_f32 v107, v108, v109
	v_add_f32_e32 v108, v102, v142
	v_exp_f32_e32 v98, v98
	v_fma_f32 v99, v99, s21, -v139
	v_add_f32_e32 v108, v103, v108
	v_exp_f32_e32 v99, v99
	v_fma_f32 v100, v100, s21, -v139
	v_add_f32_e32 v108, v104, v108
	v_exp_f32_e32 v100, v100
	v_fma_f32 v101, v101, s21, -v139
	v_add_f32_e32 v142, v105, v108
	v_exp_f32_e32 v101, v101
	v_fma_f32 v94, v94, s21, -v139
	v_cvt_pk_bf16_f32 v108, v102, v103
	v_add_f32_e32 v102, v98, v142
	v_exp_f32_e32 v94, v94
	v_fma_f32 v95, v95, s21, -v139
	v_add_f32_e32 v102, v99, v102
	v_exp_f32_e32 v95, v95
	v_fma_f32 v96, v96, s21, -v139
	v_add_f32_e32 v102, v100, v102
	v_exp_f32_e32 v96, v96
	v_fma_f32 v97, v97, s21, -v139
	v_add_f32_e32 v102, v101, v102
	v_exp_f32_e32 v97, v97
	v_cvt_pk_bf16_f32 v98, v98, v99
	v_cvt_pk_bf16_f32 v99, v100, v101
	v_add_f32_e32 v100, v94, v102
	v_add_f32_e32 v100, v95, v100
	v_add_f32_e32 v100, v96, v100
	v_fma_f32 v90, v90, s21, -v138
	v_fma_f32 v86, v86, s21, -v138
	v_fma_f32 v78, v78, s21, -v138
	v_add_f32_e32 v102, v97, v100
	v_cvt_pk_bf16_f32 v100, v94, v95
	v_or_b32_e32 v94, s5, v132
	v_exp_f32_e32 v144, v90
	v_fma_f32 v90, v91, s21, -v138
	v_exp_f32_e32 v159, v86
	v_fma_f32 v86, v87, s21, -v138
	v_exp_f32_e32 v154, v78
	v_fma_f32 v78, v79, s21, -v138
	v_exp_f32_e32 v145, v90
	v_fma_f32 v90, v92, s21, -v138
	v_exp_f32_e32 v146, v86
	v_fma_f32 v86, v88, s21, -v138
	v_exp_f32_e32 v151, v78
	v_fma_f32 v78, v80, s21, -v138
	v_mul_u32_u24_e32 v143, 0x48, v94
	v_exp_f32_e32 v147, v90
	v_fma_f32 v90, v93, s21, -v138
	v_exp_f32_e32 v148, v86
	v_fma_f32 v86, v89, s21, -v138
	v_exp_f32_e32 v152, v78
	v_fma_f32 v78, v81, s21, -v138
	v_lshl_add_u32 v142, v143, 1, v130
	v_cvt_pk_bf16_f32 v101, v96, v97
	v_exp_f32_e32 v149, v90
	v_exp_f32_e32 v150, v86
	v_exp_f32_e32 v155, v78
	ds_read_b64_tr_b16 v[80:81], v142 offset:55552
	ds_read_b64_tr_b16 v[78:79], v142 offset:53248
	ds_read_b64_tr_b16 v[88:89], v142 offset:55584
	ds_read_b64_tr_b16 v[86:87], v142 offset:53280
	ds_read_b64_tr_b16 v[90:91], v142 offset:57856
	ds_read_b64_tr_b16 v[92:93], v142 offset:60160
	ds_read_b64_tr_b16 v[96:97], v142 offset:60192
	ds_read_b64_tr_b16 v[94:95], v142 offset:57888
	v_fma_f32 v82, v82, s21, -v138
	v_exp_f32_e32 v153, v82
	v_fma_f32 v82, v83, s21, -v138
	v_exp_f32_e32 v156, v82
	v_fma_f32 v82, v84, s21, -v138
	v_exp_f32_e32 v157, v82
	v_fma_f32 v82, v85, s21, -v138
	v_exp_f32_e32 v158, v82
	v_cvt_pk_bf16_f32 v109, v104, v105
	v_add_f32_e32 v141, v141, v102
	v_cvt_pk_bf16_f32 v82, v144, v145
	v_cvt_pk_bf16_f32 v83, v147, v149
	v_cvt_pk_bf16_f32 v84, v153, v156
	v_cvt_pk_bf16_f32 v85, v157, v158
	v_cvt_pk_bf16_f32 v102, v159, v146
	v_cvt_pk_bf16_f32 v103, v148, v150
	v_cvt_pk_bf16_f32 v104, v154, v151
	v_cvt_pk_bf16_f32 v105, v152, v155
	s_setprio 2
	s_waitcnt lgkmcnt(6)
	v_mfma_f32_16x16x32_bf16 v[74:77], v[78:81], v[106:109], v[74:77]
	v_mfma_f32_16x16x32_bf16 v[58:61], v[78:81], v[82:85], v[58:61]
	s_waitcnt lgkmcnt(4)
	v_mfma_f32_16x16x32_bf16 v[70:73], v[86:89], v[106:109], v[70:73]
	v_mfma_f32_16x16x32_bf16 v[78:81], v[86:89], v[82:85], v[54:57]
	s_waitcnt lgkmcnt(2)
	v_mfma_f32_16x16x32_bf16 v[74:77], v[90:93], v[98:101], v[74:77]
	v_mfma_f32_16x16x32_bf16 v[58:61], v[90:93], v[102:105], v[58:61]
	s_waitcnt lgkmcnt(0)
	v_mfma_f32_16x16x32_bf16 v[54:57], v[94:97], v[98:101], v[70:73]
	v_mfma_f32_16x16x32_bf16 v[70:73], v[94:97], v[102:105], v[78:81]
	s_setprio 1
	s_nop 1
	ds_read_b64_tr_b16 v[80:81], v142 offset:55616
	ds_read_b64_tr_b16 v[78:79], v142 offset:53312
	ds_read_b64_tr_b16 v[88:89], v142 offset:55648
	ds_read_b64_tr_b16 v[86:87], v142 offset:53344
	ds_read_b64_tr_b16 v[90:91], v142 offset:57920
	ds_read_b64_tr_b16 v[92:93], v142 offset:60224
	ds_read_b64_tr_b16 v[96:97], v142 offset:60256
	ds_read_b64_tr_b16 v[94:95], v142 offset:57952
	s_setprio 2
	s_waitcnt lgkmcnt(6)
	v_mfma_f32_16x16x32_bf16 v[66:69], v[78:81], v[106:109], v[66:69]
	v_mfma_f32_16x16x32_bf16 v[78:81], v[78:81], v[82:85], v[50:53]
	s_waitcnt lgkmcnt(2)
	v_mfma_f32_16x16x32_bf16 v[50:53], v[90:93], v[98:101], v[66:69]
	v_mfma_f32_16x16x32_bf16 v[66:69], v[90:93], v[102:105], v[78:81]
	v_mfma_f32_16x16x32_bf16 v[62:65], v[86:89], v[106:109], v[62:65]
	v_mfma_f32_16x16x32_bf16 v[78:81], v[86:89], v[82:85], v[46:49]
	s_waitcnt lgkmcnt(0)
	v_mfma_f32_16x16x32_bf16 v[46:49], v[94:97], v[98:101], v[62:65]
	v_mfma_f32_16x16x32_bf16 v[62:65], v[94:97], v[102:105], v[78:81]
	s_setprio 1
	v_add_u32_e32 v160, v0, v160
	s_nop 2
	ds_read_b128 v[78:81], v160 offset:13312
	ds_read_b128 v[82:85], v160 offset:13376
	ds_read_b128 v[86:89], v160 offset:13440
	ds_read_b128 v[94:97], v160 offset:16640
	ds_read_b128 v[98:101], v160 offset:16704
	ds_read_b128 v[102:105], v160 offset:16768
	s_setprio 2
	s_waitcnt lgkmcnt(5)
	v_mfma_f32_16x16x32_bf16 v[90:93], v[78:81], v[2:5], 0
	v_mfma_f32_16x16x32_bf16 v[78:81], v[78:81], v[26:29], 0
	s_waitcnt lgkmcnt(4)
	v_mfma_f32_16x16x32_bf16 v[90:93], v[82:85], v[6:9], v[90:93]
	v_mfma_f32_16x16x32_bf16 v[78:81], v[82:85], v[30:33], v[78:81]
	s_waitcnt lgkmcnt(3)
	v_mfma_f32_16x16x32_bf16 v[106:109], v[86:89], v[38:41], v[90:93]
	v_mfma_f32_16x16x32_bf16 v[90:93], v[86:89], v[42:45], v[78:81]
	s_waitcnt lgkmcnt(2)
	v_mfma_f32_16x16x32_bf16 v[78:81], v[94:97], v[2:5], 0
	v_mfma_f32_16x16x32_bf16 v[82:85], v[94:97], v[26:29], 0
	s_waitcnt lgkmcnt(1)
	v_mfma_f32_16x16x32_bf16 v[78:81], v[98:101], v[6:9], v[78:81]
	v_mfma_f32_16x16x32_bf16 v[82:85], v[98:101], v[30:33], v[82:85]
	s_waitcnt lgkmcnt(0)
	v_mfma_f32_16x16x32_bf16 v[98:101], v[102:105], v[38:41], v[78:81]
	v_mfma_f32_16x16x32_bf16 v[82:85], v[102:105], v[42:45], v[82:85]
	s_setprio 1
	s_nop 2
	ds_read_b128 v[78:81], v160 offset:19968
	ds_read_b128 v[86:89], v160 offset:20032
	ds_read_b128 v[94:97], v160 offset:20096
	ds_read_b128 v[164:167], v160 offset:23296
	ds_read_b128 v[168:171], v160 offset:23360
	ds_read_b128 v[172:175], v160 offset:23424
	s_setprio 2
	s_waitcnt lgkmcnt(5)
	v_mfma_f32_16x16x32_bf16 v[102:105], v[78:81], v[2:5], 0
	v_mfma_f32_16x16x32_bf16 v[78:81], v[78:81], v[26:29], 0
	s_waitcnt lgkmcnt(4)
	v_mfma_f32_16x16x32_bf16 v[102:105], v[86:89], v[6:9], v[102:105]
	v_mfma_f32_16x16x32_bf16 v[78:81], v[86:89], v[30:33], v[78:81]
	s_waitcnt lgkmcnt(3)
	v_mfma_f32_16x16x32_bf16 v[102:105], v[94:97], v[38:41], v[102:105]
	v_mfma_f32_16x16x32_bf16 v[86:89], v[94:97], v[42:45], v[78:81]
	s_waitcnt lgkmcnt(2)
	v_mfma_f32_16x16x32_bf16 v[78:81], v[164:167], v[2:5], 0
	v_mfma_f32_16x16x32_bf16 v[94:97], v[164:167], v[26:29], 0
	s_waitcnt lgkmcnt(1)
	v_mfma_f32_16x16x32_bf16 v[78:81], v[168:171], v[6:9], v[78:81]
	v_mfma_f32_16x16x32_bf16 v[164:167], v[168:171], v[30:33], v[94:97]
	s_waitcnt lgkmcnt(0)
	v_mfma_f32_16x16x32_bf16 v[94:97], v[172:175], v[38:41], v[78:81]
	v_mfma_f32_16x16x32_bf16 v[78:81], v[172:175], v[42:45], v[164:167]
	s_setprio 1
	v_max3_f32 v160, v106, s18, v107
	v_max3_f32 v160, v160, v108, v109
	v_max3_f32 v160, v160, v98, v99
	v_max3_f32 v160, v160, v100, v101
	v_max3_f32 v160, v160, v102, v103
	v_max3_f32 v160, v160, v104, v105
	v_max3_f32 v160, v160, v94, v95
	v_max3_f32 v160, v160, v96, v97
	v_mul_f32_e32 v160, 0x3e16c740, v160
	v_mov_b32_e32 v161, v160
	s_nop 1
	v_permlane16_swap_b32_e32 v161, v160
	v_max_f32_e32 v160, v160, v161
	v_mov_b32_e32 v161, v160
	s_nop 1
	v_permlane32_swap_b32_e32 v161, v160
	v_max_f32_e32 v160, v160, v161
	v_add_f32_e32 v161, 0x41000000, v139
	v_cmp_gt_f32_e32 vcc, v160, v161
	s_cbranch_vccz .Lmlahi_BB0_565
	v_max_f32_e32 v160, v160, v160
	v_max_f32_e32 v161, v139, v139
	v_max_f32_e32 v161, v161, v160
	v_sub_f32_e32 v139, v139, v161
	v_exp_f32_e32 v160, v139
	v_mov_b32_e32 v139, v161
	v_mul_f32_e32 v141, v141, v160
	v_pk_mul_f32 v[76:77], v[76:77], v[160:161] op_sel_hi:[1,0]
	v_pk_mul_f32 v[74:75], v[74:75], v[160:161] op_sel_hi:[1,0]
	v_pk_mul_f32 v[56:57], v[56:57], v[160:161] op_sel_hi:[1,0]
	v_pk_mul_f32 v[54:55], v[54:55], v[160:161] op_sel_hi:[1,0]
	v_pk_mul_f32 v[52:53], v[52:53], v[160:161] op_sel_hi:[1,0]
	v_pk_mul_f32 v[50:51], v[50:51], v[160:161] op_sel_hi:[1,0]
	v_pk_mul_f32 v[48:49], v[48:49], v[160:161] op_sel_hi:[1,0]
	v_pk_mul_f32 v[46:47], v[46:47], v[160:161] op_sel_hi:[1,0]
	v_xor_b32_e32 v160, 0x80000000, v161
	s_branch .Lmlahi_BB0_566

.Lmlahi_BB0_569:
	v_lshl_add_u32 v180, v143, 1, v210
	v_fmamk_f32 v106, v106, 0x3e16c740, v160
	v_fmamk_f32 v107, v107, 0x3e16c740, v160
	v_fmamk_f32 v108, v108, 0x3e16c740, v160
	v_fmamk_f32 v109, v109, 0x3e16c740, v160
	v_fmamk_f32 v98, v98, 0x3e16c740, v160
	v_fmamk_f32 v99, v99, 0x3e16c740, v160
	v_fmamk_f32 v100, v100, 0x3e16c740, v160
	v_fmamk_f32 v101, v101, 0x3e16c740, v160
	v_fmamk_f32 v102, v102, 0x3e16c740, v160
	v_fmamk_f32 v103, v103, 0x3e16c740, v160
	v_fmamk_f32 v104, v104, 0x3e16c740, v160
	v_fmamk_f32 v105, v105, 0x3e16c740, v160
	v_fmamk_f32 v94, v94, 0x3e16c740, v160
	v_fmamk_f32 v95, v95, 0x3e16c740, v160
	v_fmamk_f32 v96, v96, 0x3e16c740, v160
	v_fmac_f32_e32 v160, 0x3e16c740, v97
	v_fmamk_f32 v90, v90, 0x3e16c740, v144
	v_fmamk_f32 v91, v91, 0x3e16c740, v144
	v_fmamk_f32 v92, v92, 0x3e16c740, v144
	v_fmamk_f32 v93, v93, 0x3e16c740, v144
	v_fmamk_f32 v82, v82, 0x3e16c740, v144
	v_fmamk_f32 v83, v83, 0x3e16c740, v144
	v_fmamk_f32 v84, v84, 0x3e16c740, v144
	v_fmamk_f32 v85, v85, 0x3e16c740, v144
	v_fmamk_f32 v86, v86, 0x3e16c740, v144
	v_fmamk_f32 v87, v87, 0x3e16c740, v144
	v_fmamk_f32 v88, v88, 0x3e16c740, v144
	v_fmamk_f32 v89, v89, 0x3e16c740, v144
	v_fmamk_f32 v78, v78, 0x3e16c740, v144
	v_fmamk_f32 v79, v79, 0x3e16c740, v144
	v_fmamk_f32 v80, v80, 0x3e16c740, v144
	v_fmac_f32_e32 v144, 0x3e16c740, v81
	v_add_u32_e32 v143, v133, v180
	v_exp_f32_e32 v97, v160
	v_exp_f32_e32 v81, v144
	ds_read_b64_tr_b16 v[160:161], v142 offset:64768
	ds_read_b64_tr_b16 v[158:159], v142 offset:62464
	ds_read_b64_tr_b16 v[166:167], v142 offset:64800
	ds_read_b64_tr_b16 v[164:165], v142 offset:62496
	v_add_u32_e32 v144, v134, v180
	ds_read_b64_tr_b16 v[168:169], v143
	ds_read_b64_tr_b16 v[170:171], v143 offset:2304
	ds_read_b64_tr_b16 v[172:173], v144
	ds_read_b64_tr_b16 v[174:175], v144 offset:2304
	v_exp_f32_e32 v106, v106
	v_exp_f32_e32 v107, v107
	v_exp_f32_e32 v108, v108
	v_exp_f32_e32 v109, v109
	v_exp_f32_e32 v98, v98
	v_exp_f32_e32 v99, v99
	v_exp_f32_e32 v100, v100
	v_exp_f32_e32 v101, v101
	v_exp_f32_e32 v102, v102
	v_exp_f32_e32 v103, v103
	v_exp_f32_e32 v104, v104
	v_exp_f32_e32 v105, v105
	v_exp_f32_e32 v94, v94
	v_exp_f32_e32 v95, v95
	v_exp_f32_e32 v96, v96
	v_exp_f32_e32 v90, v90
	v_exp_f32_e32 v91, v91
	v_exp_f32_e32 v92, v92
	v_exp_f32_e32 v93, v93
	v_exp_f32_e32 v82, v82
	v_exp_f32_e32 v83, v83
	v_exp_f32_e32 v84, v84
	v_exp_f32_e32 v85, v85
	v_exp_f32_e32 v86, v86
	v_exp_f32_e32 v87, v87
	v_exp_f32_e32 v88, v88
	v_exp_f32_e32 v89, v89
	v_exp_f32_e32 v78, v78
	v_exp_f32_e32 v79, v79
	v_exp_f32_e32 v80, v80
	v_cvt_pk_bf16_f32 v146, v106, v107
	v_cvt_pk_bf16_f32 v147, v108, v109
	v_cvt_pk_bf16_f32 v148, v98, v99
	v_cvt_pk_bf16_f32 v149, v100, v101
	v_cvt_pk_bf16_f32 v150, v102, v103
	v_cvt_pk_bf16_f32 v151, v104, v105
	v_cvt_pk_bf16_f32 v152, v94, v95
	v_cvt_pk_bf16_f32 v153, v96, v97
	v_cvt_pk_bf16_f32 v154, v90, v91
	v_cvt_pk_bf16_f32 v155, v92, v93
	v_cvt_pk_bf16_f32 v156, v82, v83
	v_cvt_pk_bf16_f32 v157, v84, v85
	v_cvt_pk_bf16_f32 v176, v86, v87
	v_cvt_pk_bf16_f32 v177, v88, v89
	v_cvt_pk_bf16_f32 v178, v78, v79
	v_cvt_pk_bf16_f32 v179, v80, v81
	s_setprio 2
	s_waitcnt lgkmcnt(6)
	v_mfma_f32_16x16x32_bf16 v[74:77], v[158:161], v[146:149], v[74:77]
	v_mfma_f32_16x16x32_bf16 v[58:61], v[158:161], v[154:157], v[58:61]
	s_waitcnt lgkmcnt(4)
	v_mfma_f32_16x16x32_bf16 v[54:57], v[164:167], v[146:149], v[54:57]
	v_mfma_f32_16x16x32_bf16 v[158:161], v[164:167], v[154:157], v[70:73]
	s_waitcnt lgkmcnt(2)
	v_mfma_f32_16x16x32_bf16 v[74:77], v[168:171], v[150:153], v[74:77]
	v_mfma_f32_16x16x32_bf16 v[58:61], v[168:171], v[176:179], v[58:61]
	s_waitcnt lgkmcnt(0)
	v_mfma_f32_16x16x32_bf16 v[70:73], v[172:175], v[150:153], v[54:57]
	v_mfma_f32_16x16x32_bf16 v[54:57], v[172:175], v[176:179], v[158:161]
	s_setprio 1
	v_add_u32_e32 v166, v135, v180
	v_add_u32_e32 v170, v136, v180
	ds_read_b64_tr_b16 v[160:161], v142 offset:64832
	ds_read_b64_tr_b16 v[158:159], v142 offset:62528
	ds_read_b64_tr_b16 v[144:145], v142 offset:64864
	ds_read_b64_tr_b16 v[142:143], v142 offset:62560
	ds_read_b64_tr_b16 v[164:165], v166
	ds_read_b64_tr_b16 v[166:167], v166 offset:2304
	ds_read_b64_tr_b16 v[168:169], v170
	ds_read_b64_tr_b16 v[170:171], v170 offset:2304
	s_setprio 2
	s_waitcnt lgkmcnt(6)
	v_mfma_f32_16x16x32_bf16 v[50:53], v[158:161], v[146:149], v[50:53]
	v_mfma_f32_16x16x32_bf16 v[158:161], v[158:161], v[154:157], v[66:69]
	s_waitcnt lgkmcnt(4)
	v_mfma_f32_16x16x32_bf16 v[46:49], v[142:145], v[146:149], v[46:49]
	v_mfma_f32_16x16x32_bf16 v[142:145], v[142:145], v[154:157], v[62:65]
	s_waitcnt lgkmcnt(2)
	v_mfma_f32_16x16x32_bf16 v[66:69], v[164:167], v[150:153], v[50:53]
	v_mfma_f32_16x16x32_bf16 v[50:53], v[164:167], v[176:179], v[158:161]
	s_waitcnt lgkmcnt(0)
	v_mfma_f32_16x16x32_bf16 v[62:65], v[168:171], v[150:153], v[46:49]
	v_mfma_f32_16x16x32_bf16 v[46:49], v[168:171], v[176:179], v[142:145]
	s_setprio 1
	s_andn2_b64 vcc, exec, s[2:3]
	s_cbranch_vccnz .Lmlahi_BB0_556
	s_xor_b32 s5, s5, 0x80
	s_cmp_eq_u32 s5, 0
	s_cbranch_scc1 .Lmlahi_mla_stage_buf0
	s_waitcnt vmcnt(4)
	ds_write_b128 v224, v[10:13] offset:26624
	s_waitcnt vmcnt(3)
	ds_write_b128 v229, v[14:17] offset:53248
	s_waitcnt vmcnt(2)
	ds_write_b128 v226, v[18:21] offset:26624
	s_waitcnt vmcnt(1)
	ds_write_b128 v230, v[22:25] offset:53248
	s_waitcnt vmcnt(0)
	ds_write_b128 v228, v[34:37] offset:26752
	s_branch .Lmlahi_BB0_556
